# v142 + the grid barrier after the last layer's P8 is skipped (nothing follows it)
# speedup vs baseline: 1.0050x; 1.0016x over previous
.LBB0_1049:
	v_readlane_b32 s2, v255, 25
	s_cmp_eq_u32 s2, 3
	s_cbranch_scc1 .LBB0_1100
	v_readlane_b32 s2, v253, 1
	v_readlane_b32 s3, v253, 2
	s_waitcnt vmcnt(0)
	s_waitcnt lgkmcnt(0)
	s_barrier
	s_mov_b64 s[0:1], exec
	v_readlane_b32 s4, v253, 5
	v_readlane_b32 s5, v253, 6
	s_and_b64 s[4:5], s[0:1], s[4:5]
	s_mov_b64 exec, s[4:5]
	s_cbranch_execnz .LBB0_1050
	s_getpc_b64 s[98:99]
